# attnA: one static s_setprio 1 for waves 4-7 during the tile loop (younger half), on top of the wide-store version
# speedup vs baseline: 1.0009x; 1.0009x over previous
; #define LAS __attribute__((address_space(3)))
; __device__ __forceinline__ void attnA_unit(const P2Ctx& C, int b, int h, int qb) {
;     ...
;     for (int kt = 1; kt < NT; ++kt) {
;         if (kt + 2 < NT && !(pf & 16)) A_DMA(kt + 2);
;         if (kt < ntw) {
;             A_QK(kt)
;             if (!(pf & 4)) {
;             const LAS unsigned char* vimg = lds + ((kt - 1) & 3) * 32768 + 16384;
;             VRaw va;
;             v_issue<4>(vimg, 0, lane, va);
.LaA_wd_6:
	s_barrier
	s_mov_b32 s14, 1
	s_cmp_eq_u32 s8, 0
	s_cbranch_scc1 .LaA_noprio
	s_setprio 1
.LaA_noprio:
.LaA_loop:
	s_cmp_lt_u32 s14, s13
	s_cbranch_scc0 .LaA_pvonly
	s_and_b32 s6, s14, 3
	s_lshl_b32 s6, s6, 15
	s_add_i32 s7, s14, -1
	s_and_b32 s7, s7, 3
	s_lshl_b32 s7, s7, 15
	v_add_u32_e32 v248, s6, v200
	v_add_u32_e32 v249, s6, v201
	v_add_u32_e32 v250, s6, v202
	v_add_u32_e32 v251, s6, v203
	v_add_u32_e32 v237, s7, v204
	ds_read_b128 v[100:103], v248
	ds_read_b128 v[104:107], v248 offset:4096
	ds_read_b128 v[108:111], v249
	ds_read_b128 v[112:115], v249 offset:4096
	ds_read_b128 v[116:119], v250
	ds_read_b128 v[120:123], v250 offset:4096
	ds_read_b128 v[124:127], v251
	ds_read_b128 v[128:131], v251 offset:4096
	s_cmp_lt_u32 s24, s12
	s_cbranch_scc0 .LaA_nodma_7
	s_and_b32 s6, s24, 3
	s_lshl_b32 s6, s6, 15
	s_add_i32 s7, s6, s22
	s_mov_b32 m0, s7
	s_add_u32 s20, s16, 0x80
	s_addc_u32 s21, s17, 0
	s_add_i32 s29, s6, s23
	global_load_lds_dwordx4 v197, s[16:17]
	s_add_i32 m0, s7, 0x2000
	s_add_u32 s16, s16, 0x20000
	s_addc_u32 s17, s17, 0
	s_nop 0
	global_load_lds_dwordx4 v197, s[20:21]
	s_mov_b32 m0, s29
	s_add_u32 s20, s18, 0x80
	s_addc_u32 s21, s19, 0
	s_nop 0
	global_load_lds_dwordx4 v198, s[18:19]
	s_add_i32 m0, s29, 0x400
	s_add_u32 s18, s18, 0x20000
	s_addc_u32 s19, s19, 0
	s_add_i32 s24, s24, 1
	global_load_lds_dwordx4 v198, s[20:21]

; #define LAS __attribute__((address_space(3)))
; __device__ __forceinline__ void attnA_unit(const P2Ctx& C, int b, int h, int qb) {
;     ...
;     l += __shfl_xor(l, 32);
;     const float inv = 1.0f / l;
;     LAS float* X2 = (LAS float*)(lds + 65536);
;     if (comp == 1) {
; #pragma unroll
;         for (int cb = 0; cb < 4; ++cb)
; #pragma unroll
;             for (int r = 0; r < 16; ++r) X2[((qs * 4 + cb) * 16 + r) * 64 + lane] = o[cb][r] * inv;
;     }
.LaA_nofinalpv_14:
	s_waitcnt lgkmcnt(0)
	s_barrier
	v_mov_b32_e32 v243, v241
	s_nop 1
	v_permlane32_swap_b32 v243, v241
	v_add_f32_e32 v241, v243, v241
	v_rcp_f32_e32 v241, v241
	s_lshl_b32 s6, s9, 14
	s_add_i32 s6, s6, 0x10000
	v_lshlrev_b32_e32 v2, 2, v219
	v_add_u32_e32 v2, s6, v2
	s_cmp_eq_u32 s8, 0
	s_cbranch_scc1 .LaA_comp0_15
	s_nop 7
	s_nop 3
	v_mul_f32_e32 v68, v4, v241
	ds_write_b32 v2, v68 offset:0
	v_mul_f32_e32 v69, v5, v241
	ds_write_b32 v2, v69 offset:256
	v_mul_f32_e32 v68, v6, v241
	ds_write_b32 v2, v68 offset:512
	v_mul_f32_e32 v69, v7, v241
	ds_write_b32 v2, v69 offset:768
	v_mul_f32_e32 v68, v8, v241
	ds_write_b32 v2, v68 offset:1024
	v_mul_f32_e32 v69, v9, v241
	ds_write_b32 v2, v69 offset:1280
	v_mul_f32_e32 v68, v10, v241
	ds_write_b32 v2, v68 offset:1536
	v_mul_f32_e32 v69, v11, v241
	ds_write_b32 v2, v69 offset:1792
	v_mul_f32_e32 v68, v12, v241
	ds_write_b32 v2, v68 offset:2048
	v_mul_f32_e32 v69, v13, v241
	ds_write_b32 v2, v69 offset:2304
	v_mul_f32_e32 v68, v14, v241
	ds_write_b32 v2, v68 offset:2560
	v_mul_f32_e32 v69, v15, v241
	ds_write_b32 v2, v69 offset:2816
	v_mul_f32_e32 v68, v16, v241
	ds_write_b32 v2, v68 offset:3072
	v_mul_f32_e32 v69, v17, v241
	ds_write_b32 v2, v69 offset:3328
	v_mul_f32_e32 v68, v18, v241
	ds_write_b32 v2, v68 offset:3584
	v_mul_f32_e32 v69, v19, v241
	ds_write_b32 v2, v69 offset:3840
	v_mul_f32_e32 v68, v20, v241
	ds_write_b32 v2, v68 offset:4096
	v_mul_f32_e32 v69, v21, v241
	ds_write_b32 v2, v69 offset:4352
	v_mul_f32_e32 v68, v22, v241
	ds_write_b32 v2, v68 offset:4608
	v_mul_f32_e32 v69, v23, v241
	ds_write_b32 v2, v69 offset:4864
	v_mul_f32_e32 v68, v24, v241
	ds_write_b32 v2, v68 offset:5120
	v_mul_f32_e32 v69, v25, v241
	ds_write_b32 v2, v69 offset:5376
	v_mul_f32_e32 v68, v26, v241
	ds_write_b32 v2, v68 offset:5632
	v_mul_f32_e32 v69, v27, v241
	ds_write_b32 v2, v69 offset:5888
	v_mul_f32_e32 v68, v28, v241
	ds_write_b32 v2, v68 offset:6144
	v_mul_f32_e32 v69, v29, v241
	ds_write_b32 v2, v69 offset:6400
	v_mul_f32_e32 v68, v30, v241
	ds_write_b32 v2, v68 offset:6656
	v_mul_f32_e32 v69, v31, v241
	ds_write_b32 v2, v69 offset:6912
	v_mul_f32_e32 v68, v32, v241
	ds_write_b32 v2, v68 offset:7168
	v_mul_f32_e32 v69, v33, v241
	ds_write_b32 v2, v69 offset:7424
	v_mul_f32_e32 v68, v34, v241
	ds_write_b32 v2, v68 offset:7680
	v_mul_f32_e32 v69, v35, v241
	ds_write_b32 v2, v69 offset:7936
	v_mul_f32_e32 v68, v36, v241
	ds_write_b32 v2, v68 offset:8192
	v_mul_f32_e32 v69, v37, v241
	ds_write_b32 v2, v69 offset:8448
	v_mul_f32_e32 v68, v38, v241
	ds_write_b32 v2, v68 offset:8704
	v_mul_f32_e32 v69, v39, v241
	ds_write_b32 v2, v69 offset:8960
	v_mul_f32_e32 v68, v40, v241
	ds_write_b32 v2, v68 offset:9216
	v_mul_f32_e32 v69, v41, v241
	ds_write_b32 v2, v69 offset:9472
	v_mul_f32_e32 v68, v42, v241
	ds_write_b32 v2, v68 offset:9728
	v_mul_f32_e32 v69, v43, v241
	ds_write_b32 v2, v69 offset:9984
	v_mul_f32_e32 v68, v44, v241
	ds_write_b32 v2, v68 offset:10240
	v_mul_f32_e32 v69, v45, v241
	ds_write_b32 v2, v69 offset:10496
	v_mul_f32_e32 v68, v46, v241
	ds_write_b32 v2, v68 offset:10752
	v_mul_f32_e32 v69, v47, v241
	ds_write_b32 v2, v69 offset:11008
	v_mul_f32_e32 v68, v48, v241
	ds_write_b32 v2, v68 offset:11264
	v_mul_f32_e32 v69, v49, v241
	ds_write_b32 v2, v69 offset:11520
	v_mul_f32_e32 v68, v50, v241
	ds_write_b32 v2, v68 offset:11776
	v_mul_f32_e32 v69, v51, v241
	ds_write_b32 v2, v69 offset:12032
	v_mul_f32_e32 v68, v52, v241
	ds_write_b32 v2, v68 offset:12288
	v_mul_f32_e32 v69, v53, v241
	ds_write_b32 v2, v69 offset:12544
	v_mul_f32_e32 v68, v54, v241
	ds_write_b32 v2, v68 offset:12800
	v_mul_f32_e32 v69, v55, v241
	ds_write_b32 v2, v69 offset:13056
	v_mul_f32_e32 v68, v56, v241
	ds_write_b32 v2, v68 offset:13312
	v_mul_f32_e32 v69, v57, v241
	ds_write_b32 v2, v69 offset:13568
	v_mul_f32_e32 v68, v58, v241
	ds_write_b32 v2, v68 offset:13824
	v_mul_f32_e32 v69, v59, v241
	ds_write_b32 v2, v69 offset:14080
	v_mul_f32_e32 v68, v60, v241
	ds_write_b32 v2, v68 offset:14336
	v_mul_f32_e32 v69, v61, v241
	ds_write_b32 v2, v69 offset:14592
	v_mul_f32_e32 v68, v62, v241
	ds_write_b32 v2, v68 offset:14848
	v_mul_f32_e32 v69, v63, v241
	ds_write_b32 v2, v69 offset:15104
	v_mul_f32_e32 v68, v64, v241
	ds_write_b32 v2, v68 offset:15360
	v_mul_f32_e32 v69, v65, v241
	ds_write_b32 v2, v69 offset:15616
	v_mul_f32_e32 v68, v66, v241
	ds_write_b32 v2, v68 offset:15872
	v_mul_f32_e32 v69, v67, v241
	ds_write_b32 v2, v69 offset:16128
	s_waitcnt lgkmcnt(0)
	s_barrier
	s_branch .LaA_epiend_16
; __device__ __forceinline__ void attnA_unit(const P2Ctx& C, int b, int h, int qb) {
;     ...
;     if (comp == 1) {
; #pragma unroll
;         for (int cb = 0; cb < 4; ++cb)
; #pragma unroll
;             for (int r = 0; r < 16; ++r) X2[((qs * 4 + cb) * 16 + r) * 64 + lane] = o[cb][r] * inv;
;     }
;     __syncthreads();
	s_nop 0
	s_nop 0
	s_nop 0
	s_nop 0
	s_nop 0
	s_nop 0
	s_nop 0
	s_nop 0
	s_nop 0
	s_nop 0
	s_nop 0
	s_nop 0
	s_nop 0
	s_nop 0
	s_nop 0
	s_nop 0
	s_nop 0
	s_nop 0
	s_nop 0
	s_nop 0
	s_nop 0
	s_nop 0
	s_nop 0
	s_nop 0
	s_nop 0
	s_nop 0
	s_nop 0
	s_nop 0
	s_nop 0
	s_nop 0
	s_nop 0
	s_nop 0
	s_nop 0
	s_nop 0
	s_nop 0
	s_nop 0
	s_nop 0
	s_nop 0
	s_nop 0
	s_nop 0
	s_nop 0
	s_nop 0
	s_nop 0
	s_nop 0
	s_nop 0
	s_nop 0
	s_nop 0
	s_nop 0
	s_nop 0
	s_nop 0
	s_nop 0
	s_nop 0
	s_nop 0
	s_nop 0
	s_nop 0
	s_nop 0
	s_nop 0
	s_nop 0
	s_nop 0
	s_nop 0
	s_nop 0
	s_nop 0
	s_nop 0
	s_nop 0
	s_nop 0
	s_nop 0
	s_nop 0
	s_nop 0
	s_nop 0
	s_nop 0
	s_nop 0
	s_nop 0
	s_nop 0
	s_nop 0
	s_nop 0
	s_nop 0
	s_nop 0
	s_nop 0
	s_nop 0
	s_nop 0
	s_nop 0
	s_nop 0
	s_nop 0
	s_nop 0
	s_nop 0
	s_nop 0
	s_nop 0
	s_nop 0
	s_nop 0
	s_nop 0
	s_nop 0
	s_nop 0
	s_nop 0
	s_nop 0
	s_nop 0
	s_nop 0
	s_nop 0
	s_nop 0
	s_nop 0
	s_nop 0
	s_nop 0
	s_nop 0
	s_nop 0
	s_nop 0
	s_nop 0
	s_nop 0
	s_nop 0
	s_nop 0
	s_nop 0
	s_nop 0
	s_nop 0
	s_nop 0
	s_nop 0
	s_nop 0
	s_nop 0
	s_nop 0
	s_nop 0
	s_nop 0
	s_nop 0
	s_nop 0
	s_nop 0
	s_nop 0
	s_nop 0
	s_nop 0
	s_nop 0
	s_nop 0
	s_nop 0
	s_nop 0
	s_nop 0
	s_nop 0
	s_nop 0
	s_nop 0
	s_nop 0
	s_nop 0
	s_nop 0
	s_nop 0
	s_nop 0
	s_nop 0
	s_nop 0
	s_nop 0
	s_nop 0
	s_nop 0
	s_nop 0
	s_nop 0
	s_nop 0
	s_nop 0
	s_nop 0
	s_nop 0
	s_nop 0
	s_nop 0
	s_nop 0
	s_nop 0
	s_nop 0
	s_nop 0
	s_nop 0
	s_nop 0
	s_nop 0
	s_nop 0
	s_nop 0
	s_nop 0
	s_nop 0
	s_nop 0
	s_nop 0
	s_nop 0
	s_nop 0
	s_nop 0
	s_nop 0
	s_nop 0
	s_nop 0
	s_nop 0
	s_nop 0
	s_nop 0
	s_nop 0
	s_nop 0
	s_nop 0
	s_nop 0
	s_nop 0
	s_nop 0
	s_nop 0
	s_nop 0
	s_nop 0
	s_nop 0
	s_nop 0
	s_nop 0
	s_nop 0
	s_nop 0
	s_nop 0
	s_nop 0
	s_nop 0
	s_nop 0
	s_nop 0
	s_nop 0
	s_nop 0
	s_nop 0
	s_nop 0
	s_nop 0
	s_nop 0
	s_nop 0
	s_nop 0
	s_nop 0
	s_nop 0
	s_nop 0
	s_nop 0
	s_nop 0
	s_nop 0
	s_nop 0
	s_nop 0
	s_nop 0
	s_nop 0
	s_nop 0
	s_nop 0
	s_nop 0
	s_nop 0
	s_nop 0
	s_nop 0
	s_nop 0
	s_nop 0
	s_nop 0
	s_nop 0
	s_nop 0
	s_nop 0
	s_nop 0
	s_nop 0
	s_nop 0
	s_nop 0
	s_nop 0
	s_nop 0
	s_nop 0
	s_nop 0
	s_nop 0
	s_nop 0
	s_nop 0
	s_nop 0
	s_nop 0
	s_nop 0
	s_nop 0
	s_nop 0
	s_nop 0
	s_nop 0
	s_nop 0
	s_nop 0
	s_nop 0
	s_nop 0
	s_nop 0
	s_nop 0
	s_nop 0
	s_nop 0
	s_nop 0
	s_nop 0
	s_nop 0
	s_nop 0
	s_nop 0
	s_nop 0
	s_nop 0
	s_nop 0
	s_nop 0
	s_nop 0
	s_nop 0
	s_nop 0
	s_nop 0
	s_nop 0
	s_nop 0
	s_nop 0
	s_nop 0
	s_nop 0
	s_nop 0
	s_nop 0
	s_nop 0
	s_nop 0
	s_nop 0
	s_nop 0
	s_nop 0
	s_nop 0
	s_nop 0
	s_nop 0
	s_nop 0
	s_nop 0
	s_nop 0
	s_nop 0
	s_nop 0
	s_nop 0
	s_nop 0
	s_nop 0
	s_nop 0
	s_nop 0
	s_nop 0
	s_nop 0
	s_nop 0
	s_nop 0
	s_nop 0
	s_nop 0
	s_nop 0
	s_nop 0
	s_nop 0
	s_nop 0
	s_nop 0
	s_nop 0
	s_nop 0
	s_nop 0
	s_nop 0
	s_nop 0
	s_nop 0
	s_nop 0
	s_nop 0
	s_nop 0
	s_nop 0
	s_nop 0
	s_nop 0
	s_nop 0
	s_nop 0
	s_nop 0
	s_nop 0
	s_nop 0
	s_nop 0
	s_nop 0
	s_nop 0
	s_nop 0
	s_nop 0
	s_nop 0
	s_nop 0
	s_nop 0
	s_nop 0
	s_nop 0
	s_nop 0
	s_nop 0
	s_nop 0
	s_nop 0
	s_nop 0
	s_nop 0
	s_nop 0
	s_nop 0
	s_nop 0
	s_nop 0
	s_nop 0
	s_nop 0
	s_nop 0
	s_nop 0
	s_nop 0
	s_nop 0
	s_nop 0
	s_nop 0
	s_nop 0
	s_nop 0
	s_nop 0
	s_nop 0
	s_nop 0
	s_nop 0
	s_nop 0
	s_nop 0
	s_nop 0
	s_nop 0
	s_nop 0
	s_nop 0
	s_nop 0
	s_nop 0
	s_nop 0
	s_nop 0
	s_nop 0
	s_nop 0
	s_nop 0
	s_nop 0
	s_nop 0
	s_nop 0
	s_nop 0
	s_nop 0
	s_nop 0
	s_nop 0
	s_nop 0
	s_nop 0
	s_nop 0
	s_nop 0
	s_nop 0
	s_nop 0
	s_nop 0
	s_nop 0
	s_nop 0
	s_nop 0
	s_nop 0
	s_nop 0
	s_nop 0
	s_nop 0
	s_nop 0
	s_nop 0
	s_nop 0
	s_nop 0
	s_nop 0
	s_nop 0
	s_nop 0
	s_nop 0
	s_nop 0
	s_nop 0
	s_nop 0
	s_nop 0
	s_nop 0
	s_nop 0
	s_nop 0
	s_nop 0
	s_nop 0
	s_nop 0
	s_nop 0
	s_nop 0
	s_nop 0
	s_nop 0
	s_nop 0
	s_nop 0
	s_nop 0
	s_nop 0
	s_nop 0
	s_nop 0
	s_nop 0
	s_nop 0
	s_nop 0
	s_nop 0
	s_nop 0
	s_nop 0
	s_nop 0
	s_nop 0
	s_nop 0
	s_nop 0
	s_nop 0
	s_nop 0
	s_nop 0
	s_nop 0
	s_nop 0
	s_nop 0
	s_nop 0
	s_nop 0
	s_nop 0
	s_nop 0
	s_nop 0
	s_nop 0
	s_nop 0
	s_nop 0
	s_nop 0
	s_nop 0
	s_nop 0
	s_nop 0
	s_nop 0
	s_nop 0
	s_nop 0
	s_nop 0
	s_nop 0
	s_nop 0
	s_nop 0
	s_nop 0
	s_nop 0
	s_nop 0
	s_nop 0
	s_nop 0
	s_nop 0
	s_nop 0
	s_nop 0
	s_nop 0
	s_nop 0
	s_nop 0
	s_nop 0
	s_nop 0
	s_nop 0
	s_nop 0
	s_nop 0
	s_nop 0
	s_nop 0
	s_nop 0
	s_nop 0
	s_nop 0
	s_nop 0
	s_nop 0
	s_nop 0
	s_nop 0
	s_nop 0
	s_nop 0
	s_nop 0
	s_nop 0
	s_nop 0
	s_nop 0
	s_nop 0
	s_nop 0
	s_nop 0
	s_nop 0
	s_nop 0
	s_nop 0
	s_nop 0
	s_nop 0
	s_nop 0
	s_nop 0
	s_nop 0
	s_nop 0
	s_nop 0
	s_nop 0
	s_nop 0
	s_nop 0
	s_nop 0
	s_nop 0
	s_nop 0
	s_nop 0
	s_nop 0
	s_nop 0
	s_nop 0
	s_nop 0
	s_nop 0
	s_nop 0
	s_nop 0
	s_nop 0
	s_nop 0
	s_nop 0
	s_nop 0
	s_nop 0
	s_nop 0
	s_nop 0
	s_nop 0
	s_nop 0
	s_nop 0
	s_nop 0
	s_nop 0
	s_nop 0
	s_nop 0
	s_nop 0
	s_nop 0
	s_nop 0
	s_nop 0
	s_nop 0
	s_nop 0
	s_nop 0
	s_nop 0
	s_nop 0
	s_nop 0
	s_nop 0
	s_nop 0
	s_nop 0
	s_nop 0
	s_nop 0
	s_nop 0
	s_nop 0
	s_nop 0
	s_nop 0
	s_nop 0
	s_nop 0
	s_nop 0
	s_nop 0
	s_nop 0
	s_nop 0
	s_nop 0
	s_nop 0
	s_nop 0
	s_nop 0
	s_nop 0
	s_nop 0
	s_nop 0
	s_nop 0
	s_nop 0
	s_nop 0
	s_nop 0
	s_nop 0
	s_nop 0
	s_nop 0
	s_nop 0
	s_nop 0
	s_nop 0
	s_nop 0
	s_nop 0
	s_nop 0
	s_nop 0
	s_nop 0
	s_nop 0
	s_nop 0
	s_nop 0
	s_nop 0
	s_nop 0
	s_nop 0
	s_nop 0
	s_nop 0
	s_nop 0
	s_nop 0
	s_nop 0
	s_nop 0
	s_nop 0
	s_nop 0
	s_nop 0
	s_nop 0
	s_nop 0
	s_nop 0
	s_nop 0
	s_nop 0
	s_nop 0
	s_nop 0
	s_nop 0
	s_nop 0
	s_nop 0
	s_nop 0
	s_nop 0
	s_nop 0
	s_nop 0
	s_nop 0
	s_nop 0
	s_nop 0
	s_nop 0
	s_nop 0
	s_nop 0
	s_nop 0
	s_nop 0
	s_nop 0
	s_nop 0
	s_nop 0
	s_nop 0
	s_nop 0
	s_nop 0
	s_nop 0
	s_nop 0
	s_nop 0
	s_nop 0
	s_nop 0
	s_nop 0
	s_nop 0
	s_nop 0
	s_nop 0
	s_nop 0
	s_nop 0
	s_nop 0
	s_nop 0
	s_nop 0
	s_nop 0
	s_nop 0
	s_nop 0
	s_nop 0
	s_nop 0
	s_nop 0
	s_nop 0
	s_nop 0
	s_nop 0
	s_nop 0
	s_nop 0
	s_nop 0
	s_nop 0
	s_nop 0
	s_nop 0
	s_nop 0
	s_nop 0
	s_nop 0
	s_nop 0
	s_nop 0
	s_nop 0
	s_nop 0
	s_nop 0
	s_nop 0
	s_nop 0
	s_nop 0
	s_nop 0
	s_nop 0
	s_nop 0
	s_nop 0
	s_nop 0
	s_nop 0
	s_nop 0
	s_nop 0
	s_nop 0
	s_nop 0
	s_nop 0
	s_nop 0
	s_nop 0
	s_nop 0
	s_nop 0
	s_nop 0
	s_nop 0
	s_nop 0
	s_nop 0
	s_nop 0
	s_nop 0
	s_nop 0
	s_nop 0
	s_nop 0
	s_nop 0
	s_nop 0
	s_nop 0
	s_nop 0
	s_nop 0
	s_nop 0
	s_nop 0
	s_nop 0
; __device__ __forceinline__ void subln_store(f32x16 (&o)[4], const float* subg, bf16_t* dst  , int lane) {
;     ...
;     f32x4 sg[4][4];
; #pragma unroll
;     for (int cb = 0; cb < 4; ++cb)
; #pragma unroll
;         for (int g = 0; g < 4; ++g) sg[cb][g] = *(const f32x4*)(subg + 32 * cb + 8 * g + 4 * hi);
; __device__ __forceinline__ void attnA_unit(const P2Ctx& C, int b, int h, int qb) {
;     ...
;     if (comp == 0) {
; #pragma unroll
;         for (int cb = 0; cb < 4; ++cb)
; #pragma unroll
;             for (int r = 0; r < 16; ++r) o[cb][r] = o[cb][r] * inv - lam * X2[((qs * 4 + cb) * 16 + r) * 64 + lane];
.LaA_comp0_15:
	v_lshrrev_b32_e32 v242, 5, v219
	v_lshlrev_b32_e32 v242, 4, v242
	v_add_u32_e32 v242, 0x22a00, v242
	ds_read_b128 v[100:103], v242 offset:0
	ds_read_b128 v[104:107], v242 offset:32
	ds_read_b128 v[108:111], v242 offset:64
	ds_read_b128 v[112:115], v242 offset:96
	ds_read_b128 v[116:119], v242 offset:128
	ds_read_b128 v[120:123], v242 offset:160
	ds_read_b128 v[124:127], v242 offset:192
	ds_read_b128 v[128:131], v242 offset:224
	s_waitcnt lgkmcnt(4)
	ds_read_b128 v[132:135], v242 offset:256
	ds_read_b128 v[136:139], v242 offset:288
	ds_read_b128 v[140:143], v242 offset:320
	ds_read_b128 v[144:147], v242 offset:352
	ds_read_b128 v[148:151], v242 offset:384
	ds_read_b128 v[152:155], v242 offset:416
	ds_read_b128 v[156:159], v242 offset:448
	ds_read_b128 v[160:163], v242 offset:480
	s_waitcnt lgkmcnt(6)
	ds_read_b32 v243, v207
	s_nop 7
	s_nop 3
	v_mul_f32_e32 v4, v4, v241
	v_mul_f32_e32 v5, v5, v241
	v_mul_f32_e32 v6, v6, v241
	v_mul_f32_e32 v7, v7, v241
	v_mul_f32_e32 v8, v8, v241
	v_mul_f32_e32 v9, v9, v241
	v_mul_f32_e32 v10, v10, v241
	v_mul_f32_e32 v11, v11, v241
	v_mul_f32_e32 v12, v12, v241
	v_mul_f32_e32 v13, v13, v241
	v_mul_f32_e32 v14, v14, v241
	v_mul_f32_e32 v15, v15, v241
	v_mul_f32_e32 v16, v16, v241
	v_mul_f32_e32 v17, v17, v241
	v_mul_f32_e32 v18, v18, v241
	v_mul_f32_e32 v19, v19, v241
	v_mul_f32_e32 v20, v20, v241
	v_mul_f32_e32 v21, v21, v241
	v_mul_f32_e32 v22, v22, v241
	v_mul_f32_e32 v23, v23, v241
	v_mul_f32_e32 v24, v24, v241
	v_mul_f32_e32 v25, v25, v241
	v_mul_f32_e32 v26, v26, v241
	v_mul_f32_e32 v27, v27, v241
	v_mul_f32_e32 v28, v28, v241
	v_mul_f32_e32 v29, v29, v241
	v_mul_f32_e32 v30, v30, v241
	v_mul_f32_e32 v31, v31, v241
	v_mul_f32_e32 v32, v32, v241
	v_mul_f32_e32 v33, v33, v241
	v_mul_f32_e32 v34, v34, v241
	v_mul_f32_e32 v35, v35, v241
	v_mul_f32_e32 v36, v36, v241
	v_mul_f32_e32 v37, v37, v241
	v_mul_f32_e32 v38, v38, v241
	v_mul_f32_e32 v39, v39, v241
	v_mul_f32_e32 v40, v40, v241
	v_mul_f32_e32 v41, v41, v241
	v_mul_f32_e32 v42, v42, v241
	v_mul_f32_e32 v43, v43, v241
	v_mul_f32_e32 v44, v44, v241
	v_mul_f32_e32 v45, v45, v241
	v_mul_f32_e32 v46, v46, v241
	v_mul_f32_e32 v47, v47, v241
	v_mul_f32_e32 v48, v48, v241
	v_mul_f32_e32 v49, v49, v241
	v_mul_f32_e32 v50, v50, v241
	v_mul_f32_e32 v51, v51, v241
	v_mul_f32_e32 v52, v52, v241
	v_mul_f32_e32 v53, v53, v241
	v_mul_f32_e32 v54, v54, v241
	v_mul_f32_e32 v55, v55, v241
	v_mul_f32_e32 v56, v56, v241
	v_mul_f32_e32 v57, v57, v241
	v_mul_f32_e32 v58, v58, v241
	v_mul_f32_e32 v59, v59, v241
	v_mul_f32_e32 v60, v60, v241
	v_mul_f32_e32 v61, v61, v241
	v_mul_f32_e32 v62, v62, v241
	v_mul_f32_e32 v63, v63, v241
	v_mul_f32_e32 v64, v64, v241
	v_mul_f32_e32 v65, v65, v241
	v_mul_f32_e32 v66, v66, v241
	v_mul_f32_e32 v67, v67, v241
	s_waitcnt lgkmcnt(0)
	s_barrier
	ds_read2st64_b32 v[164:165], v2 offset0:0 offset1:1
	ds_read2st64_b32 v[166:167], v2 offset0:2 offset1:3
	ds_read2st64_b32 v[168:169], v2 offset0:4 offset1:5
	ds_read2st64_b32 v[170:171], v2 offset0:6 offset1:7
	ds_read2st64_b32 v[172:173], v2 offset0:8 offset1:9
	ds_read2st64_b32 v[174:175], v2 offset0:10 offset1:11
	ds_read2st64_b32 v[176:177], v2 offset0:12 offset1:13
	ds_read2st64_b32 v[178:179], v2 offset0:14 offset1:15
	ds_read2st64_b32 v[180:181], v2 offset0:16 offset1:17
	ds_read2st64_b32 v[182:183], v2 offset0:18 offset1:19
	ds_read2st64_b32 v[184:185], v2 offset0:20 offset1:21
	ds_read2st64_b32 v[186:187], v2 offset0:22 offset1:23
	ds_read2st64_b32 v[188:189], v2 offset0:24 offset1:25
	ds_read2st64_b32 v[190:191], v2 offset0:26 offset1:27
	ds_read2st64_b32 v[192:193], v2 offset0:28 offset1:29
	s_waitcnt lgkmcnt(8)
	ds_read2st64_b32 v[194:195], v2 offset0:30 offset1:31
	ds_read2st64_b32 v[68:69], v2 offset0:32 offset1:33
	ds_read2st64_b32 v[70:71], v2 offset0:34 offset1:35
	ds_read2st64_b32 v[72:73], v2 offset0:36 offset1:37
	ds_read2st64_b32 v[74:75], v2 offset0:38 offset1:39
	ds_read2st64_b32 v[76:77], v2 offset0:40 offset1:41
	ds_read2st64_b32 v[78:79], v2 offset0:42 offset1:43
	ds_read2st64_b32 v[80:81], v2 offset0:44 offset1:45
	ds_read2st64_b32 v[82:83], v2 offset0:46 offset1:47
	ds_read2st64_b32 v[84:85], v2 offset0:48 offset1:49
	ds_read2st64_b32 v[86:87], v2 offset0:50 offset1:51
	ds_read2st64_b32 v[88:89], v2 offset0:52 offset1:53
	ds_read2st64_b32 v[90:91], v2 offset0:54 offset1:55
	ds_read2st64_b32 v[92:93], v2 offset0:56 offset1:57
	ds_read2st64_b32 v[94:95], v2 offset0:58 offset1:59
	ds_read2st64_b32 v[96:97], v2 offset0:60 offset1:61
	ds_read2st64_b32 v[98:99], v2 offset0:62 offset1:63
	s_waitcnt lgkmcnt(0)
; __device__ __forceinline__ void subln_store(f32x16 (&o)[4], const float* subg, bf16_t* dst  , int lane) {
;     const int hi = lane >> 5;
;     float ss = 0.f;
; #pragma unroll
;     for (int cb = 0; cb < 4; ++cb)
; #pragma unroll
;         for (int r = 0; r < 16; ++r) ss += o[cb][r] * o[cb][r];
;     ss += __shfl_xor(ss, 32);
;     const float rstd = (1.0f - LAMBDA_INIT) / sqrtf(ss * (1.0f / 128.0f) + EPS);
; __device__ __forceinline__ void attnA_unit(const P2Ctx& C, int b, int h, int qb) {
;     ...
;             for (int r = 0; r < 16; ++r) o[cb][r] = o[cb][r] * inv - lam * X2[((qs * 4 + cb) * 16 + r) * 64 + lane];
;         subln_store(o, C.a->in[I_SUBG], C.AO + qrow * DM + h * 128, lane);
	v_fma_f32 v4, -v243, v164, v4
	v_fma_f32 v5, -v243, v165, v5
	v_fma_f32 v6, -v243, v166, v6
	v_fma_f32 v7, -v243, v167, v7
	v_fma_f32 v8, -v243, v168, v8
	v_fma_f32 v9, -v243, v169, v9
	v_fma_f32 v10, -v243, v170, v10
	v_fma_f32 v11, -v243, v171, v11
	v_fma_f32 v12, -v243, v172, v12
	v_fma_f32 v13, -v243, v173, v13
	v_fma_f32 v14, -v243, v174, v14
	v_fma_f32 v15, -v243, v175, v15
	v_fma_f32 v16, -v243, v176, v16
	v_fma_f32 v17, -v243, v177, v17
	v_fma_f32 v18, -v243, v178, v18
	v_fma_f32 v19, -v243, v179, v19
	v_fma_f32 v20, -v243, v180, v20
	v_fma_f32 v21, -v243, v181, v21
	v_fma_f32 v22, -v243, v182, v22
	v_fma_f32 v23, -v243, v183, v23
	v_fma_f32 v24, -v243, v184, v24
	v_fma_f32 v25, -v243, v185, v25
	v_fma_f32 v26, -v243, v186, v26
	v_fma_f32 v27, -v243, v187, v27
	v_fma_f32 v28, -v243, v188, v28
	v_fma_f32 v29, -v243, v189, v29
	v_fma_f32 v30, -v243, v190, v30
	v_fma_f32 v31, -v243, v191, v31
	v_fma_f32 v32, -v243, v192, v32
	v_fma_f32 v33, -v243, v193, v33
	v_fma_f32 v34, -v243, v194, v34
	v_fma_f32 v35, -v243, v195, v35
	v_fma_f32 v36, -v243, v68, v36
	v_fma_f32 v37, -v243, v69, v37
	v_fma_f32 v38, -v243, v70, v38
	v_fma_f32 v39, -v243, v71, v39
	v_fma_f32 v40, -v243, v72, v40
	v_fma_f32 v41, -v243, v73, v41
	v_fma_f32 v42, -v243, v74, v42
	v_fma_f32 v43, -v243, v75, v43
	v_fma_f32 v44, -v243, v76, v44
	v_fma_f32 v45, -v243, v77, v45
	v_fma_f32 v46, -v243, v78, v46
	v_fma_f32 v47, -v243, v79, v47
	v_fma_f32 v48, -v243, v80, v48
	v_fma_f32 v49, -v243, v81, v49
	v_fma_f32 v50, -v243, v82, v50
	v_fma_f32 v51, -v243, v83, v51
	v_fma_f32 v52, -v243, v84, v52
	v_fma_f32 v53, -v243, v85, v53
	v_fma_f32 v54, -v243, v86, v54
	v_fma_f32 v55, -v243, v87, v55
	v_fma_f32 v56, -v243, v88, v56
	v_fma_f32 v57, -v243, v89, v57
	v_fma_f32 v58, -v243, v90, v58
	v_fma_f32 v59, -v243, v91, v59
	v_fma_f32 v60, -v243, v92, v60
	v_fma_f32 v61, -v243, v93, v61
	v_fma_f32 v62, -v243, v94, v62
	v_fma_f32 v63, -v243, v95, v63
	v_fma_f32 v64, -v243, v96, v64
	v_fma_f32 v65, -v243, v97, v65
	v_fma_f32 v66, -v243, v98, v66
	v_fma_f32 v67, -v243, v99, v67
	v_mul_f32_e32 v245, v4, v4
	v_fmac_f32_e32 v245, v5, v5
	v_fmac_f32_e32 v245, v6, v6
	v_fmac_f32_e32 v245, v7, v7
	v_fmac_f32_e32 v245, v8, v8
	v_fmac_f32_e32 v245, v9, v9
	v_fmac_f32_e32 v245, v10, v10
	v_fmac_f32_e32 v245, v11, v11
	v_fmac_f32_e32 v245, v12, v12
	v_fmac_f32_e32 v245, v13, v13
	v_fmac_f32_e32 v245, v14, v14
	v_fmac_f32_e32 v245, v15, v15
	v_fmac_f32_e32 v245, v16, v16
	v_fmac_f32_e32 v245, v17, v17
	v_fmac_f32_e32 v245, v18, v18
	v_fmac_f32_e32 v245, v19, v19
	v_fmac_f32_e32 v245, v20, v20
	v_fmac_f32_e32 v245, v21, v21
	v_fmac_f32_e32 v245, v22, v22
	v_fmac_f32_e32 v245, v23, v23
	v_fmac_f32_e32 v245, v24, v24
	v_fmac_f32_e32 v245, v25, v25
	v_fmac_f32_e32 v245, v26, v26
	v_fmac_f32_e32 v245, v27, v27
	v_fmac_f32_e32 v245, v28, v28
	v_fmac_f32_e32 v245, v29, v29
	v_fmac_f32_e32 v245, v30, v30
	v_fmac_f32_e32 v245, v31, v31
	v_fmac_f32_e32 v245, v32, v32
	v_fmac_f32_e32 v245, v33, v33
	v_fmac_f32_e32 v245, v34, v34
	v_fmac_f32_e32 v245, v35, v35
	v_fmac_f32_e32 v245, v36, v36
	v_fmac_f32_e32 v245, v37, v37
	v_fmac_f32_e32 v245, v38, v38
	v_fmac_f32_e32 v245, v39, v39
	v_fmac_f32_e32 v245, v40, v40
	v_fmac_f32_e32 v245, v41, v41
	v_fmac_f32_e32 v245, v42, v42
	v_fmac_f32_e32 v245, v43, v43
	v_fmac_f32_e32 v245, v44, v44
	v_fmac_f32_e32 v245, v45, v45
	v_fmac_f32_e32 v245, v46, v46
	v_fmac_f32_e32 v245, v47, v47
	v_fmac_f32_e32 v245, v48, v48
	v_fmac_f32_e32 v245, v49, v49
	v_fmac_f32_e32 v245, v50, v50
	v_fmac_f32_e32 v245, v51, v51
	v_fmac_f32_e32 v245, v52, v52
	v_fmac_f32_e32 v245, v53, v53
	v_fmac_f32_e32 v245, v54, v54
	v_fmac_f32_e32 v245, v55, v55
	v_fmac_f32_e32 v245, v56, v56
	v_fmac_f32_e32 v245, v57, v57
	v_fmac_f32_e32 v245, v58, v58
	v_fmac_f32_e32 v245, v59, v59
	v_fmac_f32_e32 v245, v60, v60
	v_fmac_f32_e32 v245, v61, v61
	v_fmac_f32_e32 v245, v62, v62
	v_fmac_f32_e32 v245, v63, v63
	v_fmac_f32_e32 v245, v64, v64
	v_fmac_f32_e32 v245, v65, v65
	v_fmac_f32_e32 v245, v66, v66
	v_fmac_f32_e32 v245, v67, v67
	v_mov_b32_e32 v246, v245
	s_nop 1
	v_permlane32_swap_b32 v246, v245
	v_add_f32_e32 v245, v246, v245
	v_mov_b32_e32 v246, 0x3c000000
	v_fmaak_f32 v245, v245, v246, 0x358637bd
	v_rsq_f32_e32 v245, v245
	s_nop 0
	v_mul_f32_e32 v245, 0x3f4ccccd, v245
	s_lshl_b32 s6, s11, 11
	s_add_i32 s6, s6, s15
	s_lshl_b32 s6, s6, 11
	s_lshl_b32 s7, s81, 1
	s_add_i32 s6, s6, s7
	s_add_u32 s20, s70, s6
	s_addc_u32 s21, s71, 0
	v_and_b32_e32 v242, 31, v219
	v_lshlrev_b32_e32 v242, 11, v242
	v_lshrrev_b32_e32 v243, 5, v219
	v_lshl_add_u32 v242, v243, 4, v242
	s_waitcnt vmcnt(0)
; __device__ __forceinline__ unsigned pk_bf16(float lo, float hi) { f32x2 v = {lo, hi}; bf16x2_t b = __builtin_convertvector(v, bf16x2_t); return __builtin_bit_cast(unsigned, b); }
; __device__ __forceinline__ void subln_store(f32x16 (&o)[4], const float* subg, bf16_t* dst  , int lane) {
;     ...
;     for (int cb = 0; cb < 4; ++cb)
; #pragma unroll
;         for (int g = 0; g < 4; ++g) { const int dv0 = 32 * cb + 8 * g + 4 * hi; const f32x4 s4 = sg[cb][g];
;             u32x2 w; w.x = pk_bf16(o[cb][4 * g + 0] * rstd * s4[0], o[cb][4 * g + 1] * rstd * s4[1]); w.y = pk_bf16(o[cb][4 * g + 2] * rstd * s4[2], o[cb][4 * g + 3] * rstd * s4[3]);
;             *(u32x2*)(dst + dv0) = w; }
	v_mul_f32_e32 v4, v4, v245
	v_mul_f32_e32 v5, v5, v245
	v_mul_f32_e32 v6, v6, v245
	v_mul_f32_e32 v7, v7, v245
	v_mul_f32_e32 v4, v4, v100
	v_mul_f32_e32 v5, v5, v101
	v_mul_f32_e32 v6, v6, v102
	v_mul_f32_e32 v7, v7, v103
	v_mul_f32_e32 v8, v8, v245
	v_mul_f32_e32 v9, v9, v245
	v_mul_f32_e32 v10, v10, v245
	v_mul_f32_e32 v11, v11, v245
	v_mul_f32_e32 v8, v8, v104
	v_mul_f32_e32 v9, v9, v105
	v_mul_f32_e32 v10, v10, v106
	v_mul_f32_e32 v11, v11, v107
	v_cvt_pk_bf16_f32 v68, v4, v5
	v_cvt_pk_bf16_f32 v69, v6, v7
	v_cvt_pk_bf16_f32 v70, v8, v9
	v_cvt_pk_bf16_f32 v71, v10, v11
	s_nop 1
	v_permlane32_swap_b32 v68, v70
	v_permlane32_swap_b32 v69, v71
	global_store_dwordx4 v242, v[68:71], s[20:21] offset:0
	v_mul_f32_e32 v12, v12, v245
	v_mul_f32_e32 v13, v13, v245
	v_mul_f32_e32 v14, v14, v245
	v_mul_f32_e32 v15, v15, v245
	v_mul_f32_e32 v12, v12, v108
	v_mul_f32_e32 v13, v13, v109
	v_mul_f32_e32 v14, v14, v110
	v_mul_f32_e32 v15, v15, v111
	v_mul_f32_e32 v16, v16, v245
	v_mul_f32_e32 v17, v17, v245
	v_mul_f32_e32 v18, v18, v245
	v_mul_f32_e32 v19, v19, v245
	v_mul_f32_e32 v16, v16, v112
	v_mul_f32_e32 v17, v17, v113
	v_mul_f32_e32 v18, v18, v114
	v_mul_f32_e32 v19, v19, v115
	v_cvt_pk_bf16_f32 v72, v12, v13
	v_cvt_pk_bf16_f32 v73, v14, v15
	v_cvt_pk_bf16_f32 v74, v16, v17
	v_cvt_pk_bf16_f32 v75, v18, v19
	s_nop 1
	v_permlane32_swap_b32 v72, v74
	v_permlane32_swap_b32 v73, v75
	global_store_dwordx4 v242, v[72:75], s[20:21] offset:32
	v_mul_f32_e32 v20, v20, v245
	v_mul_f32_e32 v21, v21, v245
	v_mul_f32_e32 v22, v22, v245
	v_mul_f32_e32 v23, v23, v245
	v_mul_f32_e32 v20, v20, v116
	v_mul_f32_e32 v21, v21, v117
	v_mul_f32_e32 v22, v22, v118
	v_mul_f32_e32 v23, v23, v119
	v_mul_f32_e32 v24, v24, v245
	v_mul_f32_e32 v25, v25, v245
	v_mul_f32_e32 v26, v26, v245
	v_mul_f32_e32 v27, v27, v245
	v_mul_f32_e32 v24, v24, v120
	v_mul_f32_e32 v25, v25, v121
	v_mul_f32_e32 v26, v26, v122
	v_mul_f32_e32 v27, v27, v123
	v_cvt_pk_bf16_f32 v68, v20, v21
	v_cvt_pk_bf16_f32 v69, v22, v23
	v_cvt_pk_bf16_f32 v70, v24, v25
	v_cvt_pk_bf16_f32 v71, v26, v27
	s_nop 1
	v_permlane32_swap_b32 v68, v70
	v_permlane32_swap_b32 v69, v71
	global_store_dwordx4 v242, v[68:71], s[20:21] offset:64
	v_mul_f32_e32 v28, v28, v245
	v_mul_f32_e32 v29, v29, v245
	v_mul_f32_e32 v30, v30, v245
	v_mul_f32_e32 v31, v31, v245
	v_mul_f32_e32 v28, v28, v124
	v_mul_f32_e32 v29, v29, v125
	v_mul_f32_e32 v30, v30, v126
	v_mul_f32_e32 v31, v31, v127
	v_mul_f32_e32 v32, v32, v245
	v_mul_f32_e32 v33, v33, v245
	v_mul_f32_e32 v34, v34, v245
	v_mul_f32_e32 v35, v35, v245
	v_mul_f32_e32 v32, v32, v128
	v_mul_f32_e32 v33, v33, v129
	v_mul_f32_e32 v34, v34, v130
	v_mul_f32_e32 v35, v35, v131
	v_cvt_pk_bf16_f32 v72, v28, v29
	v_cvt_pk_bf16_f32 v73, v30, v31
	v_cvt_pk_bf16_f32 v74, v32, v33
	v_cvt_pk_bf16_f32 v75, v34, v35
	s_nop 1
	v_permlane32_swap_b32 v72, v74
	v_permlane32_swap_b32 v73, v75
	global_store_dwordx4 v242, v[72:75], s[20:21] offset:96
	v_mul_f32_e32 v36, v36, v245
	v_mul_f32_e32 v37, v37, v245
	v_mul_f32_e32 v38, v38, v245
	v_mul_f32_e32 v39, v39, v245
	v_mul_f32_e32 v36, v36, v132
	v_mul_f32_e32 v37, v37, v133
	v_mul_f32_e32 v38, v38, v134
	v_mul_f32_e32 v39, v39, v135
	v_mul_f32_e32 v40, v40, v245
	v_mul_f32_e32 v41, v41, v245
	v_mul_f32_e32 v42, v42, v245
	v_mul_f32_e32 v43, v43, v245
	v_mul_f32_e32 v40, v40, v136
	v_mul_f32_e32 v41, v41, v137
	v_mul_f32_e32 v42, v42, v138
	v_mul_f32_e32 v43, v43, v139
	v_cvt_pk_bf16_f32 v68, v36, v37
	v_cvt_pk_bf16_f32 v69, v38, v39
	v_cvt_pk_bf16_f32 v70, v40, v41
	v_cvt_pk_bf16_f32 v71, v42, v43
	s_nop 1
	v_permlane32_swap_b32 v68, v70
	v_permlane32_swap_b32 v69, v71
	global_store_dwordx4 v242, v[68:71], s[20:21] offset:128
	v_mul_f32_e32 v44, v44, v245
	v_mul_f32_e32 v45, v45, v245
	v_mul_f32_e32 v46, v46, v245
	v_mul_f32_e32 v47, v47, v245
	v_mul_f32_e32 v44, v44, v140
	v_mul_f32_e32 v45, v45, v141
	v_mul_f32_e32 v46, v46, v142
	v_mul_f32_e32 v47, v47, v143
	v_mul_f32_e32 v48, v48, v245
	v_mul_f32_e32 v49, v49, v245
	v_mul_f32_e32 v50, v50, v245
	v_mul_f32_e32 v51, v51, v245
	v_mul_f32_e32 v48, v48, v144
	v_mul_f32_e32 v49, v49, v145
	v_mul_f32_e32 v50, v50, v146
	v_mul_f32_e32 v51, v51, v147
	v_cvt_pk_bf16_f32 v72, v44, v45
	v_cvt_pk_bf16_f32 v73, v46, v47
	v_cvt_pk_bf16_f32 v74, v48, v49
	v_cvt_pk_bf16_f32 v75, v50, v51
	s_nop 1
	v_permlane32_swap_b32 v72, v74
	v_permlane32_swap_b32 v73, v75
	global_store_dwordx4 v242, v[72:75], s[20:21] offset:160
	v_mul_f32_e32 v52, v52, v245
	v_mul_f32_e32 v53, v53, v245
	v_mul_f32_e32 v54, v54, v245
	v_mul_f32_e32 v55, v55, v245
	v_mul_f32_e32 v52, v52, v148
	v_mul_f32_e32 v53, v53, v149
	v_mul_f32_e32 v54, v54, v150
	v_mul_f32_e32 v55, v55, v151
	v_mul_f32_e32 v56, v56, v245
	v_mul_f32_e32 v57, v57, v245
	v_mul_f32_e32 v58, v58, v245
	v_mul_f32_e32 v59, v59, v245
	v_mul_f32_e32 v56, v56, v152
	v_mul_f32_e32 v57, v57, v153
	v_mul_f32_e32 v58, v58, v154
	v_mul_f32_e32 v59, v59, v155
	v_cvt_pk_bf16_f32 v68, v52, v53
	v_cvt_pk_bf16_f32 v69, v54, v55
	v_cvt_pk_bf16_f32 v70, v56, v57
	v_cvt_pk_bf16_f32 v71, v58, v59
	s_nop 1
	v_permlane32_swap_b32 v68, v70
	v_permlane32_swap_b32 v69, v71
	global_store_dwordx4 v242, v[68:71], s[20:21] offset:192
	v_mul_f32_e32 v60, v60, v245
	v_mul_f32_e32 v61, v61, v245
	v_mul_f32_e32 v62, v62, v245
	v_mul_f32_e32 v63, v63, v245
	v_mul_f32_e32 v60, v60, v156
	v_mul_f32_e32 v61, v61, v157
	v_mul_f32_e32 v62, v62, v158
	v_mul_f32_e32 v63, v63, v159
	v_mul_f32_e32 v64, v64, v245
	v_mul_f32_e32 v65, v65, v245
	v_mul_f32_e32 v66, v66, v245
	v_mul_f32_e32 v67, v67, v245
	v_mul_f32_e32 v64, v64, v160
	v_mul_f32_e32 v65, v65, v161
	v_mul_f32_e32 v66, v66, v162
	v_mul_f32_e32 v67, v67, v163
	v_cvt_pk_bf16_f32 v72, v60, v61
	v_cvt_pk_bf16_f32 v73, v62, v63
	v_cvt_pk_bf16_f32 v74, v64, v65
	v_cvt_pk_bf16_f32 v75, v66, v67
	s_nop 1
	v_permlane32_swap_b32 v72, v74
	v_permlane32_swap_b32 v73, v75
	global_store_dwordx4 v242, v[72:75], s[20:21] offset:224
